# v72 with the per-step priorities exchanged in the main attention loops: MFMA runs at priority 2, softmax VALU at priority 1 (loads stay 0)
# speedup vs baseline: 1.0198x; 1.0198x over previous
; #define LAS __attribute__((address_space(3)))
; DI void expsum(f32x16& p, float& l_reg, bf16x8& pa0, bf16x8& pa1) {
; #pragma unroll
;     for (int r = 0; r < 16; ++r) p[r] = __builtin_amdgcn_exp2f(p[r]);
;     float ps = 0.f;
; #pragma unroll
;     for (int r = 0; r < 16; ++r) ps += p[r];
;     l_reg += ps; asm volatile("" : "+v"(l_reg));
;     ...
;     ATT_PK4(p, 0, pa0); ATT_PK4(p, 8, pa1);
;     ...
; }
; DI int v_rd_base(int lane) { return ((lane & 3) << 3) | (((lane >> 2) & 3) << 6) | (((lane >> 4) & 1) << 5) | (((lane >> 5) & 1) << 8); }
; template <int OFF> DI s16x4 tr_read(int vb) { s16x4 r; asm volatile("ds_read_b64_tr_b16 %0, %1 offset:%2" : "=&v"(r) : "v"(vb), "i"(OFF) : "memory"); return r; }
; template <int H> DI void v_reads(s16x4* vf, int vb) {
;     vf[0] = tr_read<v_rd_off(0, 2 * H, 0)>(vb); vf[1] = tr_read<v_rd_off(0, 2 * H, 1)>(vb); vf[2] = tr_read<v_rd_off(0, 2 * H + 1, 0)>(vb); vf[3] = tr_read<v_rd_off(0, 2 * H + 1, 1)>(vb);
;     vf[4] = tr_read<v_rd_off(1, 2 * H, 0)>(vb); vf[5] = tr_read<v_rd_off(1, 2 * H, 1)>(vb); vf[6] = tr_read<v_rd_off(1, 2 * H + 1, 0)>(vb); vf[7] = tr_read<v_rd_off(1, 2 * H + 1, 1)>(vb);
;     vf[8] = tr_read<v_rd_off(2, 2 * H, 0)>(vb); vf[9] = tr_read<v_rd_off(2, 2 * H, 1)>(vb); vf[10] = tr_read<v_rd_off(2, 2 * H + 1, 0)>(vb); vf[11] = tr_read<v_rd_off(2, 2 * H + 1, 1)>(vb);
;     vf[12] = tr_read<v_rd_off(3, 2 * H, 0)>(vb); vf[13] = tr_read<v_rd_off(3, 2 * H, 1)>(vb); vf[14] = tr_read<v_rd_off(3, 2 * H + 1, 0)>(vb); vf[15] = tr_read<v_rd_off(3, 2 * H + 1, 1)>(vb);
; }
; DI void pv_mma(f32x16* o, const s16x4* vf, bf16x8 pa0, bf16x8 pa1) {
;     ...
; #pragma unroll
;     for (int d0 = 0; d0 < 4; ++d0) {
;         o[d0] = __builtin_amdgcn_mfma_f32_32x32x16_bf16(pa0, ATT_PK(vf[4 * d0], vf[4 * d0 + 1]), o[d0], 0, 0, 0);
;         o[d0] = __builtin_amdgcn_mfma_f32_32x32x16_bf16(pa1, ATT_PK(vf[4 * d0 + 2], vf[4 * d0 + 3]), o[d0], 0, 0, 0); }
;     ...
; }
; template <int DQK, int D0A, int D0B> DI void k_reads(bf16x8* kf, const LAS unsigned char* Ks, int half, int r32, int hi) {
; #pragma unroll
;     for (int d0 = D0A; d0 < D0B; ++d0) kf[d0 - D0A] = *(const LAS bf16x8*)(Ks + half * (32 * DQK * 2) + kswz<DQK>(r32, (d0 * 16 + hi * 8) * 2));
; }
; template <int D0A, int D0B> DI void qk_mma(f32x16& p, const bf16x8* kf, const bf16x8* qr) {
; #pragma unroll
;     for (int d0 = D0A; d0 < D0B; ++d0) {
.Lhw_d0_b_n1922:
	ds_read_b128 v[122:125], v196 offset:4096
	ds_read_b128 v[132:135], v197 offset:4096
	s_lshl_b32 s2, s1, 14
	ds_read_b128 v[136:139], v198 offset:4096
	ds_read_b128 v[140:143], v199 offset:4096
	v_add_u32_e32 v121, s2, v106
	ds_read_b64_tr_b16 v[144:145], v121 offset:0
	ds_read_b64_tr_b16 v[146:147], v121 offset:0x800
	ds_read_b64_tr_b16 v[148:149], v121 offset:0x1000
	ds_read_b64_tr_b16 v[150:151], v121 offset:0x1800
	ds_read_b64_tr_b16 v[152:153], v121 offset:0x200
	ds_read_b64_tr_b16 v[154:155], v121 offset:0xa00
	ds_read_b64_tr_b16 v[156:157], v121 offset:0x1200
	ds_read_b64_tr_b16 v[158:159], v121 offset:0x1a00
	ds_read_b64_tr_b16 v[162:163], v121 offset:0x400
	ds_read_b64_tr_b16 v[164:165], v121 offset:0xc00
	ds_read_b64_tr_b16 v[166:167], v121 offset:0x1400
	ds_read_b64_tr_b16 v[168:169], v121 offset:0x1c00
	ds_read_b64_tr_b16 v[170:171], v121 offset:0x600
	ds_read_b64_tr_b16 v[172:173], v121 offset:0xe00
	ds_read_b64_tr_b16 v[174:175], v121 offset:0x1600
	ds_read_b64_tr_b16 v[176:177], v121 offset:0x1e00
	s_setprio 1
	v_exp_f32_e32 v64, v64
	v_exp_f32_e32 v65, v65
	v_exp_f32_e32 v66, v66
	v_exp_f32_e32 v67, v67
	v_exp_f32_e32 v68, v68
	v_exp_f32_e32 v69, v69
	v_add_f32_e32 v126, v65, v64
	v_exp_f32_e32 v70, v70
	v_add_f32_e32 v126, v66, v126
	v_exp_f32_e32 v71, v71
	v_add_f32_e32 v126, v67, v126
	v_exp_f32_e32 v72, v72
	v_add_f32_e32 v126, v68, v126
	v_exp_f32_e32 v73, v73
	v_add_f32_e32 v126, v69, v126
	v_exp_f32_e32 v74, v74
	v_add_f32_e32 v126, v70, v126
	v_exp_f32_e32 v75, v75
	v_add_f32_e32 v126, v71, v126
	v_exp_f32_e32 v76, v76
	v_add_f32_e32 v126, v72, v126
	v_exp_f32_e32 v77, v77
	v_add_f32_e32 v126, v73, v126
	v_exp_f32_e32 v78, v78
	v_add_f32_e32 v126, v74, v126
	v_exp_f32_e32 v79, v79
	v_add_f32_e32 v126, v75, v126
	v_add_f32_e32 v126, v76, v126
	v_add_f32_e32 v126, v77, v126
	v_add_f32_e32 v126, v78, v126
	v_add_f32_e32 v126, v79, v126
	v_add_f32_e32 v120, v126, v120
	v_cvt_pk_bf16_f32 v64, v64, v65
	v_cvt_pk_bf16_f32 v65, v66, v67
	v_cvt_pk_bf16_f32 v66, v68, v69
	v_cvt_pk_bf16_f32 v67, v70, v71
	v_cvt_pk_bf16_f32 v68, v72, v73
	v_cvt_pk_bf16_f32 v69, v74, v75
	v_cvt_pk_bf16_f32 v70, v76, v77
	v_cvt_pk_bf16_f32 v71, v78, v79
	s_waitcnt lgkmcnt(0)
	s_setprio 2
	v_mfma_f32_32x32x16_bf16 v[0:15], v[64:67], v[144:147], v[0:15]
	s_sub_i32 s3, s0, s98
	s_cmp_lt_u32 s3, s100
	v_mfma_f32_32x32x16_bf16 v[48:63], v[64:67], v[152:155], v[48:63]
	v_mfma_f32_32x32x16_bf16 v[32:47], v[64:67], v[162:165], v[32:47]
	v_mfma_f32_32x32x16_bf16 v[16:31], v[64:67], v[170:173], v[16:31]
	v_mfma_f32_32x32x16_bf16 v[0:15], v[68:71], v[148:151], v[0:15]
	v_mfma_f32_32x32x16_bf16 v[48:63], v[68:71], v[156:159], v[48:63]
	v_mfma_f32_32x32x16_bf16 v[32:47], v[68:71], v[166:169], v[32:47]
	v_mfma_f32_32x32x16_bf16 v[16:31], v[68:71], v[174:177], v[16:31]
	v_mfma_f32_32x32x16_bf16 v[64:79], v[122:125], v[92:95], 0
	v_mfma_f32_32x32x16_bf16 v[64:79], v[132:135], v[88:91], v[64:79]
	v_mfma_f32_32x32x16_bf16 v[64:79], v[136:139], v[84:87], v[64:79]
	v_mfma_f32_32x32x16_bf16 v[64:79], v[140:143], v[80:83], v[64:79]
	s_setprio 0
	s_cbranch_scc1 .Lhw_d0_b_dtd0bias1
.Lhw_d0_b_n1924:
	s_add_i32 s3, s22, 0xffffc000
	s_and_b32 s3, s3, 0x6000
	v_add_u32_e32 v196, s3, v107
	v_add_u32_e32 v197, s3, v108
	v_add_u32_e32 v198, s3, v109
	v_add_u32_e32 v199, s3, v110
	ds_read_b128 v[124:127], v196
	ds_read_b128 v[132:135], v197
	ds_read_b128 v[136:139], v198
	ds_read_b128 v[140:143], v199
	ds_read_b64_tr_b16 v[144:145], v121 offset:0x2000
	ds_read_b64_tr_b16 v[146:147], v121 offset:0x2800
	ds_read_b64_tr_b16 v[148:149], v121 offset:0x3000
	ds_read_b64_tr_b16 v[150:151], v121 offset:0x3800
	ds_read_b64_tr_b16 v[152:153], v121 offset:0x2200
	ds_read_b64_tr_b16 v[154:155], v121 offset:0x2a00
	ds_read_b64_tr_b16 v[156:157], v121 offset:0x3200
	ds_read_b64_tr_b16 v[158:159], v121 offset:0x3a00
	ds_read_b64_tr_b16 v[162:163], v121 offset:0x2400
	ds_read_b64_tr_b16 v[164:165], v121 offset:0x2c00
	ds_read_b64_tr_b16 v[166:167], v121 offset:0x3400
	ds_read_b64_tr_b16 v[168:169], v121 offset:0x3c00
	ds_read_b64_tr_b16 v[170:171], v121 offset:0x2600
	ds_read_b64_tr_b16 v[172:173], v121 offset:0x2e00
	ds_read_b64_tr_b16 v[174:175], v121 offset:0x3600
	ds_read_b64_tr_b16 v[176:177], v121 offset:0x3e00
	s_setprio 1
	v_exp_f32_e32 v64, v64
	v_exp_f32_e32 v65, v65
	v_exp_f32_e32 v66, v66
	v_exp_f32_e32 v67, v67
	v_exp_f32_e32 v68, v68
	v_exp_f32_e32 v69, v69
	v_add_f32_e32 v121, v65, v64
	v_exp_f32_e32 v70, v70
	v_add_f32_e32 v121, v66, v121
	v_exp_f32_e32 v71, v71
	v_add_f32_e32 v121, v67, v121
	v_exp_f32_e32 v72, v72
	v_add_f32_e32 v121, v68, v121
	v_exp_f32_e32 v73, v73
	v_add_f32_e32 v121, v69, v121
	v_exp_f32_e32 v74, v74
	v_add_f32_e32 v121, v70, v121
	v_exp_f32_e32 v75, v75
	v_add_f32_e32 v121, v71, v121
	v_exp_f32_e32 v76, v76
	v_add_f32_e32 v121, v72, v121
	v_exp_f32_e32 v77, v77
	v_add_f32_e32 v121, v73, v121
	v_exp_f32_e32 v78, v78
	v_add_f32_e32 v121, v74, v121
	v_exp_f32_e32 v79, v79
	v_add_f32_e32 v121, v75, v121
	v_add_f32_e32 v121, v76, v121
	v_add_f32_e32 v121, v77, v121
	v_add_f32_e32 v121, v78, v121
	v_add_f32_e32 v121, v79, v121
	v_add_f32_e32 v120, v120, v121
	v_cvt_pk_bf16_f32 v64, v64, v65
	v_cvt_pk_bf16_f32 v65, v66, v67
	v_cvt_pk_bf16_f32 v66, v68, v69
	v_cvt_pk_bf16_f32 v67, v70, v71
	v_cvt_pk_bf16_f32 v68, v72, v73
	v_cvt_pk_bf16_f32 v69, v74, v75
	v_cvt_pk_bf16_f32 v70, v76, v77
	v_cvt_pk_bf16_f32 v71, v78, v79
	s_waitcnt lgkmcnt(0)
	s_setprio 2
	s_waitcnt vmcnt(3)
	s_barrier
	v_mfma_f32_32x32x16_bf16 v[0:15], v[64:67], v[144:147], v[0:15]
	s_sub_i32 s74, s0, s55
	s_cmp_lt_u32 s74, s100
	v_mfma_f32_32x32x16_bf16 v[48:63], v[64:67], v[152:155], v[48:63]
	v_mfma_f32_32x32x16_bf16 v[32:47], v[64:67], v[162:165], v[32:47]
	v_mfma_f32_32x32x16_bf16 v[16:31], v[64:67], v[170:173], v[16:31]
	v_mfma_f32_32x32x16_bf16 v[0:15], v[68:71], v[148:151], v[0:15]
	v_mfma_f32_32x32x16_bf16 v[48:63], v[68:71], v[156:159], v[48:63]
	v_mfma_f32_32x32x16_bf16 v[32:47], v[68:71], v[166:169], v[32:47]
	v_mfma_f32_32x32x16_bf16 v[16:31], v[68:71], v[174:177], v[16:31]
	v_mfma_f32_32x32x16_bf16 v[64:79], v[124:127], v[92:95], 0
	v_mfma_f32_32x32x16_bf16 v[64:79], v[132:135], v[88:91], v[64:79]
	v_mfma_f32_32x32x16_bf16 v[64:79], v[136:139], v[84:87], v[64:79]
	v_mfma_f32_32x32x16_bf16 v[64:79], v[140:143], v[80:83], v[64:79]
	s_cbranch_scc1 .Lhw_d0_b_dtd0bias2

; #define LAS __attribute__((address_space(3)))
; DI void expsum(f32x16& p, float& l_reg, bf16x8& pa0, bf16x8& pa1) {
; #pragma unroll
;     for (int r = 0; r < 16; ++r) p[r] = __builtin_amdgcn_exp2f(p[r]);
;     float ps = 0.f;
; #pragma unroll
;     for (int r = 0; r < 16; ++r) ps += p[r];
;     l_reg += ps; asm volatile("" : "+v"(l_reg));
;     ...
;     ATT_PK4(p, 0, pa0); ATT_PK4(p, 8, pa1);
;     ...
; }
; DI int v_rd_base(int lane) { return ((lane & 3) << 3) | (((lane >> 2) & 3) << 6) | (((lane >> 4) & 1) << 5) | (((lane >> 5) & 1) << 8); }
; template <int OFF> DI s16x4 tr_read(int vb) { s16x4 r; asm volatile("ds_read_b64_tr_b16 %0, %1 offset:%2" : "=&v"(r) : "v"(vb), "i"(OFF) : "memory"); return r; }
; template <int H> DI void v_reads(s16x4* vf, int vb) {
;     vf[0] = tr_read<v_rd_off(0, 2 * H, 0)>(vb); vf[1] = tr_read<v_rd_off(0, 2 * H, 1)>(vb); vf[2] = tr_read<v_rd_off(0, 2 * H + 1, 0)>(vb); vf[3] = tr_read<v_rd_off(0, 2 * H + 1, 1)>(vb);
;     vf[4] = tr_read<v_rd_off(1, 2 * H, 0)>(vb); vf[5] = tr_read<v_rd_off(1, 2 * H, 1)>(vb); vf[6] = tr_read<v_rd_off(1, 2 * H + 1, 0)>(vb); vf[7] = tr_read<v_rd_off(1, 2 * H + 1, 1)>(vb);
;     vf[8] = tr_read<v_rd_off(2, 2 * H, 0)>(vb); vf[9] = tr_read<v_rd_off(2, 2 * H, 1)>(vb); vf[10] = tr_read<v_rd_off(2, 2 * H + 1, 0)>(vb); vf[11] = tr_read<v_rd_off(2, 2 * H + 1, 1)>(vb);
;     vf[12] = tr_read<v_rd_off(3, 2 * H, 0)>(vb); vf[13] = tr_read<v_rd_off(3, 2 * H, 1)>(vb); vf[14] = tr_read<v_rd_off(3, 2 * H + 1, 0)>(vb); vf[15] = tr_read<v_rd_off(3, 2 * H + 1, 1)>(vb);
; }
; DI void pv_mma(f32x16* o, const s16x4* vf, bf16x8 pa0, bf16x8 pa1) {
;     ...
; #pragma unroll
;     for (int d0 = 0; d0 < 4; ++d0) {
;         o[d0] = __builtin_amdgcn_mfma_f32_32x32x16_bf16(pa0, ATT_PK(vf[4 * d0], vf[4 * d0 + 1]), o[d0], 0, 0, 0);
;         o[d0] = __builtin_amdgcn_mfma_f32_32x32x16_bf16(pa1, ATT_PK(vf[4 * d0 + 2], vf[4 * d0 + 3]), o[d0], 0, 0, 0); }
;     ...
; }
; template <int DQK, int D0A, int D0B> DI void k_reads(bf16x8* kf, const LAS unsigned char* Ks, int half, int r32, int hi) {
; #pragma unroll
;     for (int d0 = D0A; d0 < D0B; ++d0) kf[d0 - D0A] = *(const LAS bf16x8*)(Ks + half * (32 * DQK * 2) + kswz<DQK>(r32, (d0 * 16 + hi * 8) * 2));
; }
; template <int D0A, int D0B> DI void qk_mma(f32x16& p, const bf16x8* kf, const bf16x8* qr) {
; #pragma unroll
;     for (int d0 = D0A; d0 < D0B; ++d0) {
.LBB0_1924:
	s_add_i32 s3, s22, 0xffffc000
	s_and_b32 s3, s3, 0x6000
	v_add_u32_e32 v196, s3, v107
	v_add_u32_e32 v197, s3, v108
	v_add_u32_e32 v198, s3, v109
	v_add_u32_e32 v199, s3, v110
	ds_read_b128 v[124:127], v196
	ds_read_b128 v[132:135], v197
	ds_read_b128 v[136:139], v198
	ds_read_b128 v[140:143], v199
	ds_read_b64_tr_b16 v[144:145], v121 offset:0x2000
	ds_read_b64_tr_b16 v[146:147], v121 offset:0x2800
	ds_read_b64_tr_b16 v[148:149], v121 offset:0x3000
	ds_read_b64_tr_b16 v[150:151], v121 offset:0x3800
	ds_read_b64_tr_b16 v[152:153], v121 offset:0x2200
	ds_read_b64_tr_b16 v[154:155], v121 offset:0x2a00
	ds_read_b64_tr_b16 v[156:157], v121 offset:0x3200
	ds_read_b64_tr_b16 v[158:159], v121 offset:0x3a00
	ds_read_b64_tr_b16 v[162:163], v121 offset:0x2400
	ds_read_b64_tr_b16 v[164:165], v121 offset:0x2c00
	ds_read_b64_tr_b16 v[166:167], v121 offset:0x3400
	ds_read_b64_tr_b16 v[168:169], v121 offset:0x3c00
	ds_read_b64_tr_b16 v[170:171], v121 offset:0x2600
	ds_read_b64_tr_b16 v[172:173], v121 offset:0x2e00
	ds_read_b64_tr_b16 v[174:175], v121 offset:0x3600
	ds_read_b64_tr_b16 v[176:177], v121 offset:0x3e00
	s_setprio 1
	v_exp_f32_e32 v64, v64
	v_exp_f32_e32 v65, v65
	v_exp_f32_e32 v66, v66
	v_exp_f32_e32 v67, v67
	v_exp_f32_e32 v68, v68
	v_exp_f32_e32 v69, v69
	v_add_f32_e32 v121, v65, v64
	v_exp_f32_e32 v70, v70
	v_add_f32_e32 v121, v66, v121
	v_exp_f32_e32 v71, v71
	v_add_f32_e32 v121, v67, v121
	v_exp_f32_e32 v72, v72
	v_add_f32_e32 v121, v68, v121
	v_exp_f32_e32 v73, v73
	v_add_f32_e32 v121, v69, v121
	v_exp_f32_e32 v74, v74
	v_add_f32_e32 v121, v70, v121
	v_exp_f32_e32 v75, v75
	v_add_f32_e32 v121, v71, v121
	v_exp_f32_e32 v76, v76
	v_add_f32_e32 v121, v72, v121
	v_exp_f32_e32 v77, v77
	v_add_f32_e32 v121, v73, v121
	v_exp_f32_e32 v78, v78
	v_add_f32_e32 v121, v74, v121
	v_exp_f32_e32 v79, v79
	v_add_f32_e32 v121, v75, v121
	v_add_f32_e32 v121, v76, v121
	v_add_f32_e32 v121, v77, v121
	v_add_f32_e32 v121, v78, v121
	v_add_f32_e32 v121, v79, v121
	v_add_f32_e32 v120, v120, v121
	v_cvt_pk_bf16_f32 v64, v64, v65
	v_cvt_pk_bf16_f32 v65, v66, v67
	v_cvt_pk_bf16_f32 v66, v68, v69
	v_cvt_pk_bf16_f32 v67, v70, v71
	v_cvt_pk_bf16_f32 v68, v72, v73
	v_cvt_pk_bf16_f32 v69, v74, v75
	v_cvt_pk_bf16_f32 v70, v76, v77
	v_cvt_pk_bf16_f32 v71, v78, v79
	s_waitcnt lgkmcnt(0)
	s_setprio 2
	v_mfma_f32_32x32x16_bf16 v[0:15], v[64:67], v[144:147], v[0:15]
	s_sub_i32 s74, s0, s55
	s_cmp_lt_u32 s74, s100
	v_mfma_f32_32x32x16_bf16 v[48:63], v[64:67], v[152:155], v[48:63]
	v_mfma_f32_32x32x16_bf16 v[32:47], v[64:67], v[162:165], v[32:47]
	v_mfma_f32_32x32x16_bf16 v[16:31], v[64:67], v[170:173], v[16:31]
	v_mfma_f32_32x32x16_bf16 v[0:15], v[68:71], v[148:151], v[0:15]
	v_mfma_f32_32x32x16_bf16 v[48:63], v[68:71], v[156:159], v[48:63]
	v_mfma_f32_32x32x16_bf16 v[32:47], v[68:71], v[166:169], v[32:47]
	v_mfma_f32_32x32x16_bf16 v[16:31], v[68:71], v[174:177], v[16:31]
	v_mfma_f32_32x32x16_bf16 v[64:79], v[124:127], v[92:95], 0
	v_mfma_f32_32x32x16_bf16 v[64:79], v[132:135], v[88:91], v[64:79]
	v_mfma_f32_32x32x16_bf16 v[64:79], v[136:139], v[84:87], v[64:79]
	v_mfma_f32_32x32x16_bf16 v[64:79], v[140:143], v[80:83], v[64:79]
	s_cbranch_scc1 .Ldt_d0_bias2

; #define LAS __attribute__((address_space(3)))
; DI void expsum(f32x16& p, float& l_reg, bf16x8& pa0, bf16x8& pa1) {
; #pragma unroll
;     for (int r = 0; r < 16; ++r) p[r] = __builtin_amdgcn_exp2f(p[r]);
;     float ps = 0.f;
; #pragma unroll
;     for (int r = 0; r < 16; ++r) ps += p[r];
;     l_reg += ps; asm volatile("" : "+v"(l_reg));
;     ...
;     ATT_PK4(p, 0, pa0); ATT_PK4(p, 8, pa1);
;     ...
; }
; DI int v_rd_base(int lane) { return ((lane & 3) << 3) | (((lane >> 2) & 3) << 6) | (((lane >> 4) & 1) << 5) | (((lane >> 5) & 1) << 8); }
; template <int OFF> DI s16x4 tr_read(int vb) { s16x4 r; asm volatile("ds_read_b64_tr_b16 %0, %1 offset:%2" : "=&v"(r) : "v"(vb), "i"(OFF) : "memory"); return r; }
; template <int H> DI void v_reads(s16x4* vf, int vb) {
;     vf[0] = tr_read<v_rd_off(0, 2 * H, 0)>(vb); vf[1] = tr_read<v_rd_off(0, 2 * H, 1)>(vb); vf[2] = tr_read<v_rd_off(0, 2 * H + 1, 0)>(vb); vf[3] = tr_read<v_rd_off(0, 2 * H + 1, 1)>(vb);
;     vf[4] = tr_read<v_rd_off(1, 2 * H, 0)>(vb); vf[5] = tr_read<v_rd_off(1, 2 * H, 1)>(vb); vf[6] = tr_read<v_rd_off(1, 2 * H + 1, 0)>(vb); vf[7] = tr_read<v_rd_off(1, 2 * H + 1, 1)>(vb);
;     vf[8] = tr_read<v_rd_off(2, 2 * H, 0)>(vb); vf[9] = tr_read<v_rd_off(2, 2 * H, 1)>(vb); vf[10] = tr_read<v_rd_off(2, 2 * H + 1, 0)>(vb); vf[11] = tr_read<v_rd_off(2, 2 * H + 1, 1)>(vb);
;     vf[12] = tr_read<v_rd_off(3, 2 * H, 0)>(vb); vf[13] = tr_read<v_rd_off(3, 2 * H, 1)>(vb); vf[14] = tr_read<v_rd_off(3, 2 * H + 1, 0)>(vb); vf[15] = tr_read<v_rd_off(3, 2 * H + 1, 1)>(vb);
; }
; DI void pv_mma(f32x16* o, const s16x4* vf, bf16x8 pa0, bf16x8 pa1) {
;     ...
; #pragma unroll
;     for (int d0 = 0; d0 < 4; ++d0) {
;         o[d0] = __builtin_amdgcn_mfma_f32_32x32x16_bf16(pa0, ATT_PK(vf[4 * d0], vf[4 * d0 + 1]), o[d0], 0, 0, 0);
;         o[d0] = __builtin_amdgcn_mfma_f32_32x32x16_bf16(pa1, ATT_PK(vf[4 * d0 + 2], vf[4 * d0 + 3]), o[d0], 0, 0, 0); }
;     ...
; }
; template <int DQK, int D0A, int D0B> DI void k_reads(bf16x8* kf, const LAS unsigned char* Ks, int half, int r32, int hi) {
; #pragma unroll
;     for (int d0 = D0A; d0 < D0B; ++d0) kf[d0 - D0A] = *(const LAS bf16x8*)(Ks + half * (32 * DQK * 2) + kswz<DQK>(r32, (d0 * 16 + hi * 8) * 2));
; }
; template <int D0A, int D0B> DI void qk_mma(f32x16& p, const bf16x8* kf, const bf16x8* qr) {
; #pragma unroll
;     for (int d0 = D0A; d0 < D0B; ++d0) {
.Lhw_d1_b_n1953:
	ds_read_b128 v[122:125], v196 offset:4096
	ds_read_b128 v[132:135], v197 offset:4096
	s_lshl_b32 s2, s23, 14
	ds_read_b128 v[136:139], v198 offset:4096
	ds_read_b128 v[140:143], v199 offset:4096
	v_add_u32_e32 v121, s2, v106
	ds_read_b64_tr_b16 v[144:145], v121 offset:0
	ds_read_b64_tr_b16 v[146:147], v121 offset:0x800
	ds_read_b64_tr_b16 v[148:149], v121 offset:0x1000
	ds_read_b64_tr_b16 v[150:151], v121 offset:0x1800
	ds_read_b64_tr_b16 v[152:153], v121 offset:0x200
	ds_read_b64_tr_b16 v[154:155], v121 offset:0xa00
	ds_read_b64_tr_b16 v[156:157], v121 offset:0x1200
	ds_read_b64_tr_b16 v[158:159], v121 offset:0x1a00
	ds_read_b64_tr_b16 v[162:163], v121 offset:0x400
	ds_read_b64_tr_b16 v[164:165], v121 offset:0xc00
	ds_read_b64_tr_b16 v[166:167], v121 offset:0x1400
	ds_read_b64_tr_b16 v[168:169], v121 offset:0x1c00
	ds_read_b64_tr_b16 v[170:171], v121 offset:0x600
	ds_read_b64_tr_b16 v[172:173], v121 offset:0xe00
	ds_read_b64_tr_b16 v[174:175], v121 offset:0x1600
	ds_read_b64_tr_b16 v[176:177], v121 offset:0x1e00
	s_setprio 1
	v_exp_f32_e32 v64, v64
	v_exp_f32_e32 v65, v65
	v_exp_f32_e32 v66, v66
	v_exp_f32_e32 v67, v67
	v_exp_f32_e32 v68, v68
	v_exp_f32_e32 v69, v69
	v_add_f32_e32 v126, v65, v64
	v_exp_f32_e32 v70, v70
	v_add_f32_e32 v126, v66, v126
	v_exp_f32_e32 v71, v71
	v_add_f32_e32 v126, v67, v126
	v_exp_f32_e32 v72, v72
	v_add_f32_e32 v126, v68, v126
	v_exp_f32_e32 v73, v73
	v_add_f32_e32 v126, v69, v126
	v_exp_f32_e32 v74, v74
	v_add_f32_e32 v126, v70, v126
	v_exp_f32_e32 v75, v75
	v_add_f32_e32 v126, v71, v126
	v_exp_f32_e32 v76, v76
	v_add_f32_e32 v126, v72, v126
	v_exp_f32_e32 v77, v77
	v_add_f32_e32 v126, v73, v126
	v_exp_f32_e32 v78, v78
	v_add_f32_e32 v126, v74, v126
	v_exp_f32_e32 v79, v79
	v_add_f32_e32 v126, v75, v126
	v_add_f32_e32 v126, v76, v126
	v_add_f32_e32 v126, v77, v126
	v_add_f32_e32 v126, v78, v126
	v_add_f32_e32 v126, v79, v126
	v_add_f32_e32 v120, v126, v120
	v_cvt_pk_bf16_f32 v64, v64, v65
	v_cvt_pk_bf16_f32 v65, v66, v67
	v_cvt_pk_bf16_f32 v66, v68, v69
	v_cvt_pk_bf16_f32 v67, v70, v71
	v_cvt_pk_bf16_f32 v68, v72, v73
	v_cvt_pk_bf16_f32 v69, v74, v75
	v_cvt_pk_bf16_f32 v70, v76, v77
	v_cvt_pk_bf16_f32 v71, v78, v79
	s_waitcnt lgkmcnt(0)
	s_setprio 2
	v_mfma_f32_32x32x16_bf16 v[0:15], v[64:67], v[144:147], v[0:15]
	s_sub_i32 s3, s0, s98
	s_cmp_lt_u32 s3, s100
	v_mfma_f32_32x32x16_bf16 v[48:63], v[64:67], v[152:155], v[48:63]
	v_mfma_f32_32x32x16_bf16 v[16:31], v[64:67], v[162:165], v[16:31]
	v_mfma_f32_32x32x16_bf16 v[32:47], v[64:67], v[170:173], v[32:47]
	v_mfma_f32_32x32x16_bf16 v[0:15], v[68:71], v[148:151], v[0:15]
	v_mfma_f32_32x32x16_bf16 v[48:63], v[68:71], v[156:159], v[48:63]
	v_mfma_f32_32x32x16_bf16 v[16:31], v[68:71], v[166:169], v[16:31]
	v_mfma_f32_32x32x16_bf16 v[32:47], v[68:71], v[174:177], v[32:47]
	v_mfma_f32_32x32x16_bf16 v[64:79], v[122:125], v[92:95], 0
	v_mfma_f32_32x32x16_bf16 v[64:79], v[132:135], v[88:91], v[64:79]
	v_mfma_f32_32x32x16_bf16 v[64:79], v[136:139], v[84:87], v[64:79]
	v_mfma_f32_32x32x16_bf16 v[64:79], v[140:143], v[80:83], v[64:79]
	s_setprio 0
	s_cbranch_scc1 .Lhw_d1_b_dtd1bias1
.Lhw_d1_b_n1955:
	s_add_i32 s3, s22, 0xffffc000
	s_and_b32 s3, s3, 0x6000
	v_add_u32_e32 v196, s3, v107
	v_add_u32_e32 v197, s3, v108
	v_add_u32_e32 v198, s3, v109
	v_add_u32_e32 v199, s3, v110
	ds_read_b128 v[124:127], v196
	ds_read_b128 v[132:135], v197
	ds_read_b128 v[136:139], v198
	ds_read_b128 v[140:143], v199
	ds_read_b64_tr_b16 v[144:145], v121 offset:0x2000
	ds_read_b64_tr_b16 v[146:147], v121 offset:0x2800
	ds_read_b64_tr_b16 v[148:149], v121 offset:0x3000
	ds_read_b64_tr_b16 v[150:151], v121 offset:0x3800
	ds_read_b64_tr_b16 v[152:153], v121 offset:0x2200
	ds_read_b64_tr_b16 v[154:155], v121 offset:0x2a00
	ds_read_b64_tr_b16 v[156:157], v121 offset:0x3200
	ds_read_b64_tr_b16 v[158:159], v121 offset:0x3a00
	ds_read_b64_tr_b16 v[162:163], v121 offset:0x2400
	ds_read_b64_tr_b16 v[164:165], v121 offset:0x2c00
	ds_read_b64_tr_b16 v[166:167], v121 offset:0x3400
	ds_read_b64_tr_b16 v[168:169], v121 offset:0x3c00
	ds_read_b64_tr_b16 v[170:171], v121 offset:0x2600
	ds_read_b64_tr_b16 v[172:173], v121 offset:0x2e00
	ds_read_b64_tr_b16 v[174:175], v121 offset:0x3600
	ds_read_b64_tr_b16 v[176:177], v121 offset:0x3e00
	s_setprio 1
	v_exp_f32_e32 v64, v64
	v_exp_f32_e32 v65, v65
	v_exp_f32_e32 v66, v66
	v_exp_f32_e32 v67, v67
	v_exp_f32_e32 v68, v68
	v_exp_f32_e32 v69, v69
	v_add_f32_e32 v121, v65, v64
	v_exp_f32_e32 v70, v70
	v_add_f32_e32 v121, v66, v121
	v_exp_f32_e32 v71, v71
	v_add_f32_e32 v121, v67, v121
	v_exp_f32_e32 v72, v72
	v_add_f32_e32 v121, v68, v121
	v_exp_f32_e32 v73, v73
	v_add_f32_e32 v121, v69, v121
	v_exp_f32_e32 v74, v74
	v_add_f32_e32 v121, v70, v121
	v_exp_f32_e32 v75, v75
	v_add_f32_e32 v121, v71, v121
	v_exp_f32_e32 v76, v76
	v_add_f32_e32 v121, v72, v121
	v_exp_f32_e32 v77, v77
	v_add_f32_e32 v121, v73, v121
	v_exp_f32_e32 v78, v78
	v_add_f32_e32 v121, v74, v121
	v_exp_f32_e32 v79, v79
	v_add_f32_e32 v121, v75, v121
	v_add_f32_e32 v121, v76, v121
	v_add_f32_e32 v121, v77, v121
	v_add_f32_e32 v121, v78, v121
	v_add_f32_e32 v121, v79, v121
	v_add_f32_e32 v120, v120, v121
	v_cvt_pk_bf16_f32 v64, v64, v65
	v_cvt_pk_bf16_f32 v65, v66, v67
	v_cvt_pk_bf16_f32 v66, v68, v69
	v_cvt_pk_bf16_f32 v67, v70, v71
	v_cvt_pk_bf16_f32 v68, v72, v73
	v_cvt_pk_bf16_f32 v69, v74, v75
	v_cvt_pk_bf16_f32 v70, v76, v77
	v_cvt_pk_bf16_f32 v71, v78, v79
	s_waitcnt lgkmcnt(0)
	s_setprio 2
	s_waitcnt vmcnt(3)
	s_barrier
	v_mfma_f32_32x32x16_bf16 v[0:15], v[64:67], v[144:147], v[0:15]
	s_sub_i32 s74, s0, s47
	s_cmp_lt_u32 s74, s100
	v_mfma_f32_32x32x16_bf16 v[48:63], v[64:67], v[152:155], v[48:63]
	v_mfma_f32_32x32x16_bf16 v[16:31], v[64:67], v[162:165], v[16:31]
	v_mfma_f32_32x32x16_bf16 v[32:47], v[64:67], v[170:173], v[32:47]
	v_mfma_f32_32x32x16_bf16 v[0:15], v[68:71], v[148:151], v[0:15]
	v_mfma_f32_32x32x16_bf16 v[48:63], v[68:71], v[156:159], v[48:63]
	v_mfma_f32_32x32x16_bf16 v[16:31], v[68:71], v[166:169], v[16:31]
	v_mfma_f32_32x32x16_bf16 v[32:47], v[68:71], v[174:177], v[32:47]
	v_mfma_f32_32x32x16_bf16 v[64:79], v[124:127], v[92:95], 0
	v_mfma_f32_32x32x16_bf16 v[64:79], v[132:135], v[88:91], v[64:79]
	v_mfma_f32_32x32x16_bf16 v[64:79], v[136:139], v[84:87], v[64:79]
	v_mfma_f32_32x32x16_bf16 v[64:79], v[140:143], v[80:83], v[64:79]
	s_cbranch_scc1 .Lhw_d1_b_dtd1bias2

; #define LAS __attribute__((address_space(3)))
; DI void expsum(f32x16& p, float& l_reg, bf16x8& pa0, bf16x8& pa1) {
; #pragma unroll
;     for (int r = 0; r < 16; ++r) p[r] = __builtin_amdgcn_exp2f(p[r]);
;     float ps = 0.f;
; #pragma unroll
;     for (int r = 0; r < 16; ++r) ps += p[r];
;     l_reg += ps; asm volatile("" : "+v"(l_reg));
;     ...
;     ATT_PK4(p, 0, pa0); ATT_PK4(p, 8, pa1);
;     ...
; }
; DI int v_rd_base(int lane) { return ((lane & 3) << 3) | (((lane >> 2) & 3) << 6) | (((lane >> 4) & 1) << 5) | (((lane >> 5) & 1) << 8); }
; template <int OFF> DI s16x4 tr_read(int vb) { s16x4 r; asm volatile("ds_read_b64_tr_b16 %0, %1 offset:%2" : "=&v"(r) : "v"(vb), "i"(OFF) : "memory"); return r; }
; template <int H> DI void v_reads(s16x4* vf, int vb) {
;     vf[0] = tr_read<v_rd_off(0, 2 * H, 0)>(vb); vf[1] = tr_read<v_rd_off(0, 2 * H, 1)>(vb); vf[2] = tr_read<v_rd_off(0, 2 * H + 1, 0)>(vb); vf[3] = tr_read<v_rd_off(0, 2 * H + 1, 1)>(vb);
;     vf[4] = tr_read<v_rd_off(1, 2 * H, 0)>(vb); vf[5] = tr_read<v_rd_off(1, 2 * H, 1)>(vb); vf[6] = tr_read<v_rd_off(1, 2 * H + 1, 0)>(vb); vf[7] = tr_read<v_rd_off(1, 2 * H + 1, 1)>(vb);
;     vf[8] = tr_read<v_rd_off(2, 2 * H, 0)>(vb); vf[9] = tr_read<v_rd_off(2, 2 * H, 1)>(vb); vf[10] = tr_read<v_rd_off(2, 2 * H + 1, 0)>(vb); vf[11] = tr_read<v_rd_off(2, 2 * H + 1, 1)>(vb);
;     vf[12] = tr_read<v_rd_off(3, 2 * H, 0)>(vb); vf[13] = tr_read<v_rd_off(3, 2 * H, 1)>(vb); vf[14] = tr_read<v_rd_off(3, 2 * H + 1, 0)>(vb); vf[15] = tr_read<v_rd_off(3, 2 * H + 1, 1)>(vb);
; }
; DI void pv_mma(f32x16* o, const s16x4* vf, bf16x8 pa0, bf16x8 pa1) {
;     ...
; #pragma unroll
;     for (int d0 = 0; d0 < 4; ++d0) {
;         o[d0] = __builtin_amdgcn_mfma_f32_32x32x16_bf16(pa0, ATT_PK(vf[4 * d0], vf[4 * d0 + 1]), o[d0], 0, 0, 0);
;         o[d0] = __builtin_amdgcn_mfma_f32_32x32x16_bf16(pa1, ATT_PK(vf[4 * d0 + 2], vf[4 * d0 + 3]), o[d0], 0, 0, 0); }
;     ...
; }
; template <int DQK, int D0A, int D0B> DI void k_reads(bf16x8* kf, const LAS unsigned char* Ks, int half, int r32, int hi) {
; #pragma unroll
;     for (int d0 = D0A; d0 < D0B; ++d0) kf[d0 - D0A] = *(const LAS bf16x8*)(Ks + half * (32 * DQK * 2) + kswz<DQK>(r32, (d0 * 16 + hi * 8) * 2));
; }
; template <int D0A, int D0B> DI void qk_mma(f32x16& p, const bf16x8* kf, const bf16x8* qr) {
; #pragma unroll
;     for (int d0 = D0A; d0 < D0B; ++d0) {
.LBB0_1955:
	s_add_i32 s3, s22, 0xffffc000
	s_and_b32 s3, s3, 0x6000
	v_add_u32_e32 v196, s3, v107
	v_add_u32_e32 v197, s3, v108
	v_add_u32_e32 v198, s3, v109
	v_add_u32_e32 v199, s3, v110
	ds_read_b128 v[124:127], v196
	ds_read_b128 v[132:135], v197
	ds_read_b128 v[136:139], v198
	ds_read_b128 v[140:143], v199
	ds_read_b64_tr_b16 v[144:145], v121 offset:0x2000
	ds_read_b64_tr_b16 v[146:147], v121 offset:0x2800
	ds_read_b64_tr_b16 v[148:149], v121 offset:0x3000
	ds_read_b64_tr_b16 v[150:151], v121 offset:0x3800
	ds_read_b64_tr_b16 v[152:153], v121 offset:0x2200
	ds_read_b64_tr_b16 v[154:155], v121 offset:0x2a00
	ds_read_b64_tr_b16 v[156:157], v121 offset:0x3200
	ds_read_b64_tr_b16 v[158:159], v121 offset:0x3a00
	ds_read_b64_tr_b16 v[162:163], v121 offset:0x2400
	ds_read_b64_tr_b16 v[164:165], v121 offset:0x2c00
	ds_read_b64_tr_b16 v[166:167], v121 offset:0x3400
	ds_read_b64_tr_b16 v[168:169], v121 offset:0x3c00
	ds_read_b64_tr_b16 v[170:171], v121 offset:0x2600
	ds_read_b64_tr_b16 v[172:173], v121 offset:0x2e00
	ds_read_b64_tr_b16 v[174:175], v121 offset:0x3600
	ds_read_b64_tr_b16 v[176:177], v121 offset:0x3e00
	s_setprio 1
	v_exp_f32_e32 v64, v64
	v_exp_f32_e32 v65, v65
	v_exp_f32_e32 v66, v66
	v_exp_f32_e32 v67, v67
	v_exp_f32_e32 v68, v68
	v_exp_f32_e32 v69, v69
	v_add_f32_e32 v121, v65, v64
	v_exp_f32_e32 v70, v70
	v_add_f32_e32 v121, v66, v121
	v_exp_f32_e32 v71, v71
	v_add_f32_e32 v121, v67, v121
	v_exp_f32_e32 v72, v72
	v_add_f32_e32 v121, v68, v121
	v_exp_f32_e32 v73, v73
	v_add_f32_e32 v121, v69, v121
	v_exp_f32_e32 v74, v74
	v_add_f32_e32 v121, v70, v121
	v_exp_f32_e32 v75, v75
	v_add_f32_e32 v121, v71, v121
	v_exp_f32_e32 v76, v76
	v_add_f32_e32 v121, v72, v121
	v_exp_f32_e32 v77, v77
	v_add_f32_e32 v121, v73, v121
	v_exp_f32_e32 v78, v78
	v_add_f32_e32 v121, v74, v121
	v_exp_f32_e32 v79, v79
	v_add_f32_e32 v121, v75, v121
	v_add_f32_e32 v121, v76, v121
	v_add_f32_e32 v121, v77, v121
	v_add_f32_e32 v121, v78, v121
	v_add_f32_e32 v121, v79, v121
	v_add_f32_e32 v120, v120, v121
	v_cvt_pk_bf16_f32 v64, v64, v65
	v_cvt_pk_bf16_f32 v65, v66, v67
	v_cvt_pk_bf16_f32 v66, v68, v69
	v_cvt_pk_bf16_f32 v67, v70, v71
	v_cvt_pk_bf16_f32 v68, v72, v73
	v_cvt_pk_bf16_f32 v69, v74, v75
	v_cvt_pk_bf16_f32 v70, v76, v77
	v_cvt_pk_bf16_f32 v71, v78, v79
	s_waitcnt lgkmcnt(0)
	s_setprio 2
	v_mfma_f32_32x32x16_bf16 v[0:15], v[64:67], v[144:147], v[0:15]
	s_sub_i32 s74, s0, s47
	s_cmp_lt_u32 s74, s100
	v_mfma_f32_32x32x16_bf16 v[48:63], v[64:67], v[152:155], v[48:63]
	v_mfma_f32_32x32x16_bf16 v[16:31], v[64:67], v[162:165], v[16:31]
	v_mfma_f32_32x32x16_bf16 v[32:47], v[64:67], v[170:173], v[32:47]
	v_mfma_f32_32x32x16_bf16 v[0:15], v[68:71], v[148:151], v[0:15]
	v_mfma_f32_32x32x16_bf16 v[48:63], v[68:71], v[156:159], v[48:63]
	v_mfma_f32_32x32x16_bf16 v[16:31], v[68:71], v[166:169], v[16:31]
	v_mfma_f32_32x32x16_bf16 v[32:47], v[68:71], v[174:177], v[32:47]
	v_mfma_f32_32x32x16_bf16 v[64:79], v[124:127], v[92:95], 0
	v_mfma_f32_32x32x16_bf16 v[64:79], v[132:135], v[88:91], v[64:79]
	v_mfma_f32_32x32x16_bf16 v[64:79], v[136:139], v[84:87], v[64:79]
	v_mfma_f32_32x32x16_bf16 v[64:79], v[140:143], v[80:83], v[64:79]
	s_cbranch_scc1 .Ldt_d1_bias2

; #define LAS __attribute__((address_space(3)))
; DI void expsum(f32x16& p, float& l_reg, bf16x8& pa0, bf16x8& pa1) {
; #pragma unroll
;     for (int r = 0; r < 16; ++r) p[r] = __builtin_amdgcn_exp2f(p[r]);
;     float ps = 0.f;
; #pragma unroll
;     for (int r = 0; r < 16; ++r) ps += p[r];
;     l_reg += ps; asm volatile("" : "+v"(l_reg));
;     ...
;     ATT_PK4(p, 0, pa0); ATT_PK4(p, 8, pa1);
;     ...
; }
; DI int v_rd_base(int lane) { return ((lane & 3) << 3) | (((lane >> 2) & 3) << 6) | (((lane >> 4) & 1) << 5) | (((lane >> 5) & 1) << 8); }
; template <int OFF> DI s16x4 tr_read(int vb) { s16x4 r; asm volatile("ds_read_b64_tr_b16 %0, %1 offset:%2" : "=&v"(r) : "v"(vb), "i"(OFF) : "memory"); return r; }
; template <int H> DI void v_reads(s16x4* vf, int vb) {
;     vf[0] = tr_read<v_rd_off(0, 2 * H, 0)>(vb); vf[1] = tr_read<v_rd_off(0, 2 * H, 1)>(vb); vf[2] = tr_read<v_rd_off(0, 2 * H + 1, 0)>(vb); vf[3] = tr_read<v_rd_off(0, 2 * H + 1, 1)>(vb);
;     vf[4] = tr_read<v_rd_off(1, 2 * H, 0)>(vb); vf[5] = tr_read<v_rd_off(1, 2 * H, 1)>(vb); vf[6] = tr_read<v_rd_off(1, 2 * H + 1, 0)>(vb); vf[7] = tr_read<v_rd_off(1, 2 * H + 1, 1)>(vb);
;     vf[8] = tr_read<v_rd_off(2, 2 * H, 0)>(vb); vf[9] = tr_read<v_rd_off(2, 2 * H, 1)>(vb); vf[10] = tr_read<v_rd_off(2, 2 * H + 1, 0)>(vb); vf[11] = tr_read<v_rd_off(2, 2 * H + 1, 1)>(vb);
;     vf[12] = tr_read<v_rd_off(3, 2 * H, 0)>(vb); vf[13] = tr_read<v_rd_off(3, 2 * H, 1)>(vb); vf[14] = tr_read<v_rd_off(3, 2 * H + 1, 0)>(vb); vf[15] = tr_read<v_rd_off(3, 2 * H + 1, 1)>(vb);
; }
; DI void pv_mma(f32x16* o, const s16x4* vf, bf16x8 pa0, bf16x8 pa1) {
;     ...
; #pragma unroll
;     for (int d0 = 0; d0 < 4; ++d0) {
;         o[d0] = __builtin_amdgcn_mfma_f32_32x32x16_bf16(pa0, ATT_PK(vf[4 * d0], vf[4 * d0 + 1]), o[d0], 0, 0, 0);
;         o[d0] = __builtin_amdgcn_mfma_f32_32x32x16_bf16(pa1, ATT_PK(vf[4 * d0 + 2], vf[4 * d0 + 3]), o[d0], 0, 0, 0); }
;     ...
; }
; template <int DQK, int D0A, int D0B> DI void k_reads(bf16x8* kf, const LAS unsigned char* Ks, int half, int r32, int hi) {
; #pragma unroll
;     for (int d0 = D0A; d0 < D0B; ++d0) kf[d0 - D0A] = *(const LAS bf16x8*)(Ks + half * (32 * DQK * 2) + kswz<DQK>(r32, (d0 * 16 + hi * 8) * 2));
; }
; template <int D0A, int D0B> DI void qk_mma(f32x16& p, const bf16x8* kf, const bf16x8* qr) {
; #pragma unroll
;     for (int d0 = D0A; d0 < D0B; ++d0) {
.Lhw_mla_b_n1982:
	s_and_b32 s1, s43, 3
	s_mulk_i32 s1, 0x6000
	s_add_i32 s1, s49, s1
	s_setprio 0
	s_mov_b32 m0, s1
	s_mov_b32 s0, s5
	s_mov_b32 s5, s44
	s_mov_b32 s44, s4
	s_lshl_b32 s4, s4, 14
	global_load_lds_dwordx4 v136, s[34:35]
	s_add_i32 m0, s1, 0x2000
	s_add_i32 s4, s52, s4
	global_load_lds_dwordx4 v138, s[34:35]
	s_add_i32 m0, s1, 0x4000
	s_add_i32 s6, s4, 0x400
	global_load_lds_dwordx4 v140, s[34:35]
	s_mov_b32 m0, s4
	s_add_i32 s1, s43, -3
	global_load_lds_dwordx4 v144, s[34:35]
	s_mov_b32 m0, s6
	s_nop 0
	global_load_lds_dwordx4 v142, s[34:35]
	s_and_b32 s1, s1, 3
	s_mulk_i32 s1, 0x6000
	v_add_u32_e32 v246, s1, v158
	v_add_u32_e32 v250, v246, v151
	v_add_u32_e32 v251, v246, v149
	v_add_u32_e32 v252, v246, v148
	v_add_u32_e32 v253, v246, v147
	s_lshl_b32 s1, s0, 14
	ds_read_b128 v[190:193], v250 offset:12416
	ds_read_b128 v[194:197], v251 offset:12416
	ds_read_b128 v[174:177], v250 offset:12288
	ds_read_b128 v[178:181], v251 offset:12288
	ds_read_b128 v[182:185], v252 offset:12288
	ds_read_b128 v[186:189], v253 offset:12288
	v_add_u32_e32 v254, s1, v130
	ds_read_b64_tr_b16 v[198:199], v254 offset:0
	ds_read_b64_tr_b16 v[200:201], v254 offset:0x800
	ds_read_b64_tr_b16 v[202:203], v254 offset:0x1000
	ds_read_b64_tr_b16 v[204:205], v254 offset:0x1800
	ds_read_b64_tr_b16 v[206:207], v254 offset:0x200
	ds_read_b64_tr_b16 v[208:209], v254 offset:0xa00
	ds_read_b64_tr_b16 v[210:211], v254 offset:0x1200
	ds_read_b64_tr_b16 v[212:213], v254 offset:0x1a00
	ds_read_b64_tr_b16 v[214:215], v254 offset:0x400
	ds_read_b64_tr_b16 v[216:217], v254 offset:0xc00
	ds_read_b64_tr_b16 v[218:219], v254 offset:0x1400
	ds_read_b64_tr_b16 v[220:221], v254 offset:0x1c00
	ds_read_b64_tr_b16 v[222:223], v254 offset:0x600
	ds_read_b64_tr_b16 v[224:225], v254 offset:0xe00
	ds_read_b64_tr_b16 v[226:227], v254 offset:0x1600
	ds_read_b64_tr_b16 v[228:229], v254 offset:0x1e00
	s_setprio 1
	v_exp_f32_e32 v64, v64
	v_exp_f32_e32 v65, v65
	v_exp_f32_e32 v66, v66
	v_exp_f32_e32 v67, v67
	v_exp_f32_e32 v68, v68
	v_exp_f32_e32 v69, v69
	v_add_f32_e32 v230, v65, v64
	v_exp_f32_e32 v70, v70
	v_add_f32_e32 v230, v66, v230
	v_exp_f32_e32 v71, v71
	v_add_f32_e32 v230, v67, v230
	v_exp_f32_e32 v72, v72
	v_add_f32_e32 v230, v68, v230
	v_exp_f32_e32 v73, v73
	v_add_f32_e32 v230, v69, v230
	v_exp_f32_e32 v74, v74
	v_add_f32_e32 v230, v70, v230
	v_exp_f32_e32 v75, v75
	v_add_f32_e32 v230, v71, v230
	v_exp_f32_e32 v76, v76
	v_add_f32_e32 v230, v72, v230
	v_exp_f32_e32 v77, v77
	v_add_f32_e32 v230, v73, v230
	v_exp_f32_e32 v78, v78
	v_add_f32_e32 v230, v74, v230
	v_exp_f32_e32 v79, v79
	v_add_f32_e32 v230, v75, v230
	v_add_f32_e32 v230, v76, v230
	v_add_f32_e32 v230, v77, v230
	v_add_f32_e32 v230, v78, v230
	v_add_f32_e32 v230, v79, v230
	v_add_f32_e32 v173, v173, v230
	v_cvt_pk_bf16_f32 v64, v64, v65
	v_cvt_pk_bf16_f32 v65, v66, v67
	v_cvt_pk_bf16_f32 v66, v68, v69
	v_cvt_pk_bf16_f32 v67, v70, v71
	v_cvt_pk_bf16_f32 v68, v72, v73
	v_cvt_pk_bf16_f32 v69, v74, v75
	v_cvt_pk_bf16_f32 v70, v76, v77
	v_cvt_pk_bf16_f32 v71, v78, v79
	s_waitcnt lgkmcnt(0)
	ds_read_b128 v[230:233], v252 offset:12416
	ds_read_b128 v[234:237], v253 offset:12416
	ds_read_b128 v[238:241], v250 offset:12544
	ds_read_b128 v[242:245], v251 offset:12544
	ds_read_b128 v[246:249], v252 offset:12544
	ds_read_b128 v[250:253], v253 offset:12544
	s_setprio 2
	v_mfma_f32_32x32x16_bf16 v[48:63], v[64:67], v[198:201], v[48:63]
	v_mfma_f32_32x32x16_bf16 v[32:47], v[64:67], v[206:209], v[32:47]
	v_mfma_f32_32x32x16_bf16 v[16:31], v[64:67], v[214:217], v[16:31]
	v_mfma_f32_32x32x16_bf16 v[0:15], v[64:67], v[222:225], v[0:15]
	v_mfma_f32_32x32x16_bf16 v[48:63], v[68:71], v[202:205], v[48:63]
	v_mfma_f32_32x32x16_bf16 v[32:47], v[68:71], v[210:213], v[32:47]
	v_mfma_f32_32x32x16_bf16 v[16:31], v[68:71], v[218:221], v[16:31]
	v_mfma_f32_32x32x16_bf16 v[0:15], v[68:71], v[226:229], v[0:15]
	s_waitcnt lgkmcnt(0)
	v_mfma_f32_32x32x16_bf16 v[64:79], v[174:177], v[80:83], 0
	v_mfma_f32_32x32x16_bf16 v[64:79], v[178:181], v[84:87], v[64:79]
	v_mfma_f32_32x32x16_bf16 v[64:79], v[182:185], v[88:91], v[64:79]
	v_mfma_f32_32x32x16_bf16 v[64:79], v[186:189], v[92:95], v[64:79]
	v_mfma_f32_32x32x16_bf16 v[64:79], v[190:193], v[96:99], v[64:79]
	v_mfma_f32_32x32x16_bf16 v[64:79], v[194:197], v[100:103], v[64:79]
	v_mfma_f32_32x32x16_bf16 v[64:79], v[230:233], v[104:107], v[64:79]
	v_mfma_f32_32x32x16_bf16 v[64:79], v[234:237], v[108:111], v[64:79]
	v_mfma_f32_32x32x16_bf16 v[64:79], v[238:241], v[112:115], v[64:79]
	v_mfma_f32_32x32x16_bf16 v[64:79], v[242:245], v[116:119], v[64:79]
	v_mfma_f32_32x32x16_bf16 v[64:79], v[246:249], v[120:123], v[64:79]
	v_mfma_f32_32x32x16_bf16 v[64:79], v[250:253], v[124:127], v[64:79]
	s_setprio 0
	s_add_i32 s4, s43, -2
	s_and_b32 s4, s4, 3
	s_mulk_i32 s4, 0x6000
	v_add_u32_e32 v246, s4, v158
	v_add_u32_e32 v250, v246, v151
	v_add_u32_e32 v251, v246, v149
	v_add_u32_e32 v252, v246, v148
	v_add_u32_e32 v253, v246, v147
	ds_read_b128 v[190:193], v250 offset:128
	ds_read_b128 v[194:197], v251 offset:128
	ds_read_b128 v[174:177], v250
	ds_read_b128 v[178:181], v251
	ds_read_b128 v[182:185], v252
	ds_read_b128 v[186:189], v253
	ds_read_b64_tr_b16 v[198:199], v254 offset:0x2000
	ds_read_b64_tr_b16 v[200:201], v254 offset:0x2800
	ds_read_b64_tr_b16 v[202:203], v254 offset:0x3000
	ds_read_b64_tr_b16 v[204:205], v254 offset:0x3800
	ds_read_b64_tr_b16 v[206:207], v254 offset:0x2200
	ds_read_b64_tr_b16 v[208:209], v254 offset:0x2a00
	ds_read_b64_tr_b16 v[210:211], v254 offset:0x3200
	ds_read_b64_tr_b16 v[212:213], v254 offset:0x3a00
	ds_read_b64_tr_b16 v[214:215], v254 offset:0x2400
	ds_read_b64_tr_b16 v[216:217], v254 offset:0x2c00
; #define LAS __attribute__((address_space(3)))
; DI void expsum(f32x16& p, float& l_reg, bf16x8& pa0, bf16x8& pa1) {
; #pragma unroll
;     for (int r = 0; r < 16; ++r) p[r] = __builtin_amdgcn_exp2f(p[r]);
;     float ps = 0.f;
; #pragma unroll
;     for (int r = 0; r < 16; ++r) ps += p[r];
;     l_reg += ps; asm volatile("" : "+v"(l_reg));
;     ...
;     ATT_PK4(p, 0, pa0); ATT_PK4(p, 8, pa1);
;     ...
; }
; DI int v_rd_base(int lane) { return ((lane & 3) << 3) | (((lane >> 2) & 3) << 6) | (((lane >> 4) & 1) << 5) | (((lane >> 5) & 1) << 8); }
; template <int OFF> DI s16x4 tr_read(int vb) { s16x4 r; asm volatile("ds_read_b64_tr_b16 %0, %1 offset:%2" : "=&v"(r) : "v"(vb), "i"(OFF) : "memory"); return r; }
; template <int H> DI void v_reads(s16x4* vf, int vb) {
;     vf[0] = tr_read<v_rd_off(0, 2 * H, 0)>(vb); vf[1] = tr_read<v_rd_off(0, 2 * H, 1)>(vb); vf[2] = tr_read<v_rd_off(0, 2 * H + 1, 0)>(vb); vf[3] = tr_read<v_rd_off(0, 2 * H + 1, 1)>(vb);
;     vf[4] = tr_read<v_rd_off(1, 2 * H, 0)>(vb); vf[5] = tr_read<v_rd_off(1, 2 * H, 1)>(vb); vf[6] = tr_read<v_rd_off(1, 2 * H + 1, 0)>(vb); vf[7] = tr_read<v_rd_off(1, 2 * H + 1, 1)>(vb);
;     vf[8] = tr_read<v_rd_off(2, 2 * H, 0)>(vb); vf[9] = tr_read<v_rd_off(2, 2 * H, 1)>(vb); vf[10] = tr_read<v_rd_off(2, 2 * H + 1, 0)>(vb); vf[11] = tr_read<v_rd_off(2, 2 * H + 1, 1)>(vb);
;     vf[12] = tr_read<v_rd_off(3, 2 * H, 0)>(vb); vf[13] = tr_read<v_rd_off(3, 2 * H, 1)>(vb); vf[14] = tr_read<v_rd_off(3, 2 * H + 1, 0)>(vb); vf[15] = tr_read<v_rd_off(3, 2 * H + 1, 1)>(vb);
; }
; DI void pv_mma(f32x16* o, const s16x4* vf, bf16x8 pa0, bf16x8 pa1) {
;     ...
; #pragma unroll
;     for (int d0 = 0; d0 < 4; ++d0) {
;         o[d0] = __builtin_amdgcn_mfma_f32_32x32x16_bf16(pa0, ATT_PK(vf[4 * d0], vf[4 * d0 + 1]), o[d0], 0, 0, 0);
;         o[d0] = __builtin_amdgcn_mfma_f32_32x32x16_bf16(pa1, ATT_PK(vf[4 * d0 + 2], vf[4 * d0 + 3]), o[d0], 0, 0, 0); }
;     ...
; }
; template <int DQK, int D0A, int D0B> DI void k_reads(bf16x8* kf, const LAS unsigned char* Ks, int half, int r32, int hi) {
; #pragma unroll
;     for (int d0 = D0A; d0 < D0B; ++d0) kf[d0 - D0A] = *(const LAS bf16x8*)(Ks + half * (32 * DQK * 2) + kswz<DQK>(r32, (d0 * 16 + hi * 8) * 2));
; }
; template <int D0A, int D0B> DI void qk_mma(f32x16& p, const bf16x8* kf, const bf16x8* qr) {
; #pragma unroll
;     for (int d0 = D0A; d0 < D0B; ++d0) {
	ds_read_b64_tr_b16 v[218:219], v254 offset:0x3400
	ds_read_b64_tr_b16 v[220:221], v254 offset:0x3c00
	ds_read_b64_tr_b16 v[222:223], v254 offset:0x2600
	ds_read_b64_tr_b16 v[224:225], v254 offset:0x2e00
	ds_read_b64_tr_b16 v[226:227], v254 offset:0x3600
	ds_read_b64_tr_b16 v[228:229], v254 offset:0x3e00
	s_setprio 1
	v_exp_f32_e32 v64, v64
	v_exp_f32_e32 v65, v65
	v_exp_f32_e32 v66, v66
	v_exp_f32_e32 v67, v67
	v_exp_f32_e32 v68, v68
	v_exp_f32_e32 v69, v69
	v_add_f32_e32 v230, v65, v64
	v_exp_f32_e32 v70, v70
	v_add_f32_e32 v230, v66, v230
	v_exp_f32_e32 v71, v71
	v_add_f32_e32 v230, v67, v230
	v_exp_f32_e32 v72, v72
	v_add_f32_e32 v230, v68, v230
	v_exp_f32_e32 v73, v73
	v_add_f32_e32 v230, v69, v230
	v_exp_f32_e32 v74, v74
	v_add_f32_e32 v230, v70, v230
	v_exp_f32_e32 v75, v75
	v_add_f32_e32 v230, v71, v230
	v_exp_f32_e32 v76, v76
	v_add_f32_e32 v230, v72, v230
	v_exp_f32_e32 v77, v77
	v_add_f32_e32 v230, v73, v230
	v_exp_f32_e32 v78, v78
	v_add_f32_e32 v230, v74, v230
	v_exp_f32_e32 v79, v79
	v_add_f32_e32 v230, v75, v230
	v_add_f32_e32 v230, v76, v230
	v_add_f32_e32 v230, v77, v230
	v_add_f32_e32 v230, v78, v230
	v_add_f32_e32 v230, v79, v230
	v_add_f32_e32 v173, v173, v230
	v_cvt_pk_bf16_f32 v64, v64, v65
	v_cvt_pk_bf16_f32 v65, v66, v67
	v_cvt_pk_bf16_f32 v66, v68, v69
	v_cvt_pk_bf16_f32 v67, v70, v71
	v_cvt_pk_bf16_f32 v68, v72, v73
	v_cvt_pk_bf16_f32 v69, v74, v75
	v_cvt_pk_bf16_f32 v70, v76, v77
	v_cvt_pk_bf16_f32 v71, v78, v79
	s_waitcnt lgkmcnt(0)
	ds_read_b128 v[230:233], v252 offset:128
	ds_read_b128 v[234:237], v253 offset:128
	ds_read_b128 v[238:241], v250 offset:256
	ds_read_b128 v[242:245], v251 offset:256
	ds_read_b128 v[246:249], v252 offset:256
	ds_read_b128 v[250:253], v253 offset:256
	s_setprio 2
	s_waitcnt vmcnt(5)
	s_barrier
	v_mfma_f32_32x32x16_bf16 v[48:63], v[64:67], v[198:201], v[48:63]
	v_mfma_f32_32x32x16_bf16 v[32:47], v[64:67], v[206:209], v[32:47]
	v_mfma_f32_32x32x16_bf16 v[16:31], v[64:67], v[214:217], v[16:31]
	v_mfma_f32_32x32x16_bf16 v[0:15], v[64:67], v[222:225], v[0:15]
	v_mfma_f32_32x32x16_bf16 v[48:63], v[68:71], v[202:205], v[48:63]
	v_mfma_f32_32x32x16_bf16 v[32:47], v[68:71], v[210:213], v[32:47]
	v_mfma_f32_32x32x16_bf16 v[16:31], v[68:71], v[218:221], v[16:31]
	v_mfma_f32_32x32x16_bf16 v[0:15], v[68:71], v[226:229], v[0:15]
	s_waitcnt lgkmcnt(0)
	v_mfma_f32_32x32x16_bf16 v[64:79], v[174:177], v[80:83], 0
	v_mfma_f32_32x32x16_bf16 v[64:79], v[178:181], v[84:87], v[64:79]
	v_mfma_f32_32x32x16_bf16 v[64:79], v[182:185], v[88:91], v[64:79]
	v_mfma_f32_32x32x16_bf16 v[64:79], v[186:189], v[92:95], v[64:79]
	v_mfma_f32_32x32x16_bf16 v[64:79], v[190:193], v[96:99], v[64:79]
	v_mfma_f32_32x32x16_bf16 v[64:79], v[194:197], v[100:103], v[64:79]
	v_mfma_f32_32x32x16_bf16 v[64:79], v[230:233], v[104:107], v[64:79]
	v_mfma_f32_32x32x16_bf16 v[64:79], v[234:237], v[108:111], v[64:79]
	v_mfma_f32_32x32x16_bf16 v[64:79], v[238:241], v[112:115], v[64:79]
	v_mfma_f32_32x32x16_bf16 v[64:79], v[242:245], v[116:119], v[64:79]
	v_mfma_f32_32x32x16_bf16 v[64:79], v[246:249], v[120:123], v[64:79]
	v_mfma_f32_32x32x16_bf16 v[64:79], v[250:253], v[124:127], v[64:79]
	s_add_i32 s43, s43, 1
	v_add_u32_e32 v136, s36, v136
	v_add_u32_e32 v138, s36, v138
	v_add_u32_e32 v140, s36, v140
	v_add_u32_e32 v142, s38, v142
	v_add_u32_e32 v144, s38, v144
	s_cmp_eq_u32 s43, 64
	s_mov_b32 s4, s0
	s_cbranch_scc0 .Lhw_mla_b_n1982
	s_branch .Lhw_mla_exit
.LBB0_1982:
	s_and_b32 s1, s43, 3
	s_mulk_i32 s1, 0x6000
	s_add_i32 s1, s49, s1
	s_waitcnt vmcnt(5)
	s_barrier
	s_setprio 0
	s_mov_b32 m0, s1
	s_mov_b32 s0, s5
	s_mov_b32 s5, s44
	s_mov_b32 s44, s4
	s_lshl_b32 s4, s4, 14
	global_load_lds_dwordx4 v136, s[34:35]
	s_add_i32 m0, s1, 0x2000
	s_add_i32 s4, s52, s4
	global_load_lds_dwordx4 v138, s[34:35]
	s_add_i32 m0, s1, 0x4000
	s_add_i32 s6, s4, 0x400
	global_load_lds_dwordx4 v140, s[34:35]
	s_mov_b32 m0, s4
	s_add_i32 s1, s43, -3
	global_load_lds_dwordx4 v144, s[34:35]
	s_mov_b32 m0, s6
	s_nop 0
	global_load_lds_dwordx4 v142, s[34:35]
	s_and_b32 s1, s1, 3
	s_mulk_i32 s1, 0x6000
	v_add_u32_e32 v246, s1, v158
	v_add_u32_e32 v250, v246, v151
	v_add_u32_e32 v251, v246, v149
	v_add_u32_e32 v252, v246, v148
	v_add_u32_e32 v253, v246, v147
	s_lshl_b32 s1, s0, 14
	ds_read_b128 v[190:193], v250 offset:12416
	ds_read_b128 v[194:197], v251 offset:12416
	ds_read_b128 v[174:177], v250 offset:12288
	ds_read_b128 v[178:181], v251 offset:12288
	ds_read_b128 v[182:185], v252 offset:12288
	ds_read_b128 v[186:189], v253 offset:12288
	v_add_u32_e32 v254, s1, v130
	ds_read_b64_tr_b16 v[198:199], v254 offset:0
	ds_read_b64_tr_b16 v[200:201], v254 offset:0x800
	ds_read_b64_tr_b16 v[202:203], v254 offset:0x1000
	ds_read_b64_tr_b16 v[204:205], v254 offset:0x1800
	ds_read_b64_tr_b16 v[206:207], v254 offset:0x200
	ds_read_b64_tr_b16 v[208:209], v254 offset:0xa00
	ds_read_b64_tr_b16 v[210:211], v254 offset:0x1200
	ds_read_b64_tr_b16 v[212:213], v254 offset:0x1a00
	ds_read_b64_tr_b16 v[214:215], v254 offset:0x400
	ds_read_b64_tr_b16 v[216:217], v254 offset:0xc00
	ds_read_b64_tr_b16 v[218:219], v254 offset:0x1400
	ds_read_b64_tr_b16 v[220:221], v254 offset:0x1c00
	ds_read_b64_tr_b16 v[222:223], v254 offset:0x600
	ds_read_b64_tr_b16 v[224:225], v254 offset:0xe00
	ds_read_b64_tr_b16 v[226:227], v254 offset:0x1600
	ds_read_b64_tr_b16 v[228:229], v254 offset:0x1e00
	s_setprio 1
	v_exp_f32_e32 v64, v64
	v_exp_f32_e32 v65, v65
	v_exp_f32_e32 v66, v66
	v_exp_f32_e32 v67, v67
	v_exp_f32_e32 v68, v68
	v_exp_f32_e32 v69, v69
	v_add_f32_e32 v230, v65, v64
	v_exp_f32_e32 v70, v70
	v_add_f32_e32 v230, v66, v230
	v_exp_f32_e32 v71, v71
	v_add_f32_e32 v230, v67, v230
	v_exp_f32_e32 v72, v72
	v_add_f32_e32 v230, v68, v230
	v_exp_f32_e32 v73, v73
	v_add_f32_e32 v230, v69, v230
	v_exp_f32_e32 v74, v74
	v_add_f32_e32 v230, v70, v230
	v_exp_f32_e32 v75, v75
	v_add_f32_e32 v230, v71, v230
	v_exp_f32_e32 v76, v76
	v_add_f32_e32 v230, v72, v230
	v_exp_f32_e32 v77, v77
	v_add_f32_e32 v230, v73, v230
	v_exp_f32_e32 v78, v78
	v_add_f32_e32 v230, v74, v230
	v_exp_f32_e32 v79, v79
	v_add_f32_e32 v230, v75, v230
	v_add_f32_e32 v230, v76, v230
	v_add_f32_e32 v230, v77, v230
	v_add_f32_e32 v230, v78, v230
	v_add_f32_e32 v230, v79, v230
	v_add_f32_e32 v173, v173, v230
	v_cvt_pk_bf16_f32 v64, v64, v65
	v_cvt_pk_bf16_f32 v65, v66, v67
	v_cvt_pk_bf16_f32 v66, v68, v69
	v_cvt_pk_bf16_f32 v67, v70, v71
	v_cvt_pk_bf16_f32 v68, v72, v73
	v_cvt_pk_bf16_f32 v69, v74, v75
	v_cvt_pk_bf16_f32 v70, v76, v77
	v_cvt_pk_bf16_f32 v71, v78, v79
	s_waitcnt lgkmcnt(0)
; #define LAS __attribute__((address_space(3)))
; DI void expsum(f32x16& p, float& l_reg, bf16x8& pa0, bf16x8& pa1) {
; #pragma unroll
;     for (int r = 0; r < 16; ++r) p[r] = __builtin_amdgcn_exp2f(p[r]);
;     float ps = 0.f;
; #pragma unroll
;     for (int r = 0; r < 16; ++r) ps += p[r];
;     l_reg += ps; asm volatile("" : "+v"(l_reg));
;     ...
;     ATT_PK4(p, 0, pa0); ATT_PK4(p, 8, pa1);
;     ...
; }
; DI int v_rd_base(int lane) { return ((lane & 3) << 3) | (((lane >> 2) & 3) << 6) | (((lane >> 4) & 1) << 5) | (((lane >> 5) & 1) << 8); }
; template <int OFF> DI s16x4 tr_read(int vb) { s16x4 r; asm volatile("ds_read_b64_tr_b16 %0, %1 offset:%2" : "=&v"(r) : "v"(vb), "i"(OFF) : "memory"); return r; }
; template <int H> DI void v_reads(s16x4* vf, int vb) {
;     vf[0] = tr_read<v_rd_off(0, 2 * H, 0)>(vb); vf[1] = tr_read<v_rd_off(0, 2 * H, 1)>(vb); vf[2] = tr_read<v_rd_off(0, 2 * H + 1, 0)>(vb); vf[3] = tr_read<v_rd_off(0, 2 * H + 1, 1)>(vb);
;     vf[4] = tr_read<v_rd_off(1, 2 * H, 0)>(vb); vf[5] = tr_read<v_rd_off(1, 2 * H, 1)>(vb); vf[6] = tr_read<v_rd_off(1, 2 * H + 1, 0)>(vb); vf[7] = tr_read<v_rd_off(1, 2 * H + 1, 1)>(vb);
;     vf[8] = tr_read<v_rd_off(2, 2 * H, 0)>(vb); vf[9] = tr_read<v_rd_off(2, 2 * H, 1)>(vb); vf[10] = tr_read<v_rd_off(2, 2 * H + 1, 0)>(vb); vf[11] = tr_read<v_rd_off(2, 2 * H + 1, 1)>(vb);
;     vf[12] = tr_read<v_rd_off(3, 2 * H, 0)>(vb); vf[13] = tr_read<v_rd_off(3, 2 * H, 1)>(vb); vf[14] = tr_read<v_rd_off(3, 2 * H + 1, 0)>(vb); vf[15] = tr_read<v_rd_off(3, 2 * H + 1, 1)>(vb);
; }
; DI void pv_mma(f32x16* o, const s16x4* vf, bf16x8 pa0, bf16x8 pa1) {
;     ...
; #pragma unroll
;     for (int d0 = 0; d0 < 4; ++d0) {
;         o[d0] = __builtin_amdgcn_mfma_f32_32x32x16_bf16(pa0, ATT_PK(vf[4 * d0], vf[4 * d0 + 1]), o[d0], 0, 0, 0);
;         o[d0] = __builtin_amdgcn_mfma_f32_32x32x16_bf16(pa1, ATT_PK(vf[4 * d0 + 2], vf[4 * d0 + 3]), o[d0], 0, 0, 0); }
;     ...
; }
; template <int DQK, int D0A, int D0B> DI void k_reads(bf16x8* kf, const LAS unsigned char* Ks, int half, int r32, int hi) {
; #pragma unroll
;     for (int d0 = D0A; d0 < D0B; ++d0) kf[d0 - D0A] = *(const LAS bf16x8*)(Ks + half * (32 * DQK * 2) + kswz<DQK>(r32, (d0 * 16 + hi * 8) * 2));
; }
; template <int D0A, int D0B> DI void qk_mma(f32x16& p, const bf16x8* kf, const bf16x8* qr) {
; #pragma unroll
;     for (int d0 = D0A; d0 < D0B; ++d0) {
	ds_read_b128 v[230:233], v252 offset:12416
	ds_read_b128 v[234:237], v253 offset:12416
	ds_read_b128 v[238:241], v250 offset:12544
	ds_read_b128 v[242:245], v251 offset:12544
	ds_read_b128 v[246:249], v252 offset:12544
	ds_read_b128 v[250:253], v253 offset:12544
	s_setprio 2
	v_mfma_f32_32x32x16_bf16 v[48:63], v[64:67], v[198:201], v[48:63]
	v_mfma_f32_32x32x16_bf16 v[32:47], v[64:67], v[206:209], v[32:47]
	v_mfma_f32_32x32x16_bf16 v[16:31], v[64:67], v[214:217], v[16:31]
	v_mfma_f32_32x32x16_bf16 v[0:15], v[64:67], v[222:225], v[0:15]
	v_mfma_f32_32x32x16_bf16 v[48:63], v[68:71], v[202:205], v[48:63]
	v_mfma_f32_32x32x16_bf16 v[32:47], v[68:71], v[210:213], v[32:47]
	v_mfma_f32_32x32x16_bf16 v[16:31], v[68:71], v[218:221], v[16:31]
	v_mfma_f32_32x32x16_bf16 v[0:15], v[68:71], v[226:229], v[0:15]
	s_waitcnt lgkmcnt(0)
	v_mfma_f32_32x32x16_bf16 v[64:79], v[174:177], v[80:83], 0
	v_mfma_f32_32x32x16_bf16 v[64:79], v[178:181], v[84:87], v[64:79]
	v_mfma_f32_32x32x16_bf16 v[64:79], v[182:185], v[88:91], v[64:79]
	v_mfma_f32_32x32x16_bf16 v[64:79], v[186:189], v[92:95], v[64:79]
	v_mfma_f32_32x32x16_bf16 v[64:79], v[190:193], v[96:99], v[64:79]
	v_mfma_f32_32x32x16_bf16 v[64:79], v[194:197], v[100:103], v[64:79]
	v_mfma_f32_32x32x16_bf16 v[64:79], v[230:233], v[104:107], v[64:79]
	v_mfma_f32_32x32x16_bf16 v[64:79], v[234:237], v[108:111], v[64:79]
	v_mfma_f32_32x32x16_bf16 v[64:79], v[238:241], v[112:115], v[64:79]
	v_mfma_f32_32x32x16_bf16 v[64:79], v[242:245], v[116:119], v[64:79]
	v_mfma_f32_32x32x16_bf16 v[64:79], v[246:249], v[120:123], v[64:79]
	v_mfma_f32_32x32x16_bf16 v[64:79], v[250:253], v[124:127], v[64:79]
	s_setprio 0
	s_add_i32 s4, s43, -2
	s_and_b32 s4, s4, 3
	s_mulk_i32 s4, 0x6000
	v_add_u32_e32 v246, s4, v158
	v_add_u32_e32 v250, v246, v151
	v_add_u32_e32 v251, v246, v149
	v_add_u32_e32 v252, v246, v148
	v_add_u32_e32 v253, v246, v147
	ds_read_b128 v[190:193], v250 offset:128
	ds_read_b128 v[194:197], v251 offset:128
	ds_read_b128 v[174:177], v250
	ds_read_b128 v[178:181], v251
	ds_read_b128 v[182:185], v252
	ds_read_b128 v[186:189], v253
	ds_read_b64_tr_b16 v[198:199], v254 offset:0x2000
	ds_read_b64_tr_b16 v[200:201], v254 offset:0x2800
	ds_read_b64_tr_b16 v[202:203], v254 offset:0x3000
	ds_read_b64_tr_b16 v[204:205], v254 offset:0x3800
	ds_read_b64_tr_b16 v[206:207], v254 offset:0x2200
	ds_read_b64_tr_b16 v[208:209], v254 offset:0x2a00
	ds_read_b64_tr_b16 v[210:211], v254 offset:0x3200
	ds_read_b64_tr_b16 v[212:213], v254 offset:0x3a00
	ds_read_b64_tr_b16 v[214:215], v254 offset:0x2400
	ds_read_b64_tr_b16 v[216:217], v254 offset:0x2c00
	ds_read_b64_tr_b16 v[218:219], v254 offset:0x3400
	ds_read_b64_tr_b16 v[220:221], v254 offset:0x3c00
	ds_read_b64_tr_b16 v[222:223], v254 offset:0x2600
	ds_read_b64_tr_b16 v[224:225], v254 offset:0x2e00
	ds_read_b64_tr_b16 v[226:227], v254 offset:0x3600
	ds_read_b64_tr_b16 v[228:229], v254 offset:0x3e00
	s_setprio 1
	v_exp_f32_e32 v64, v64
	v_exp_f32_e32 v65, v65
	v_exp_f32_e32 v66, v66
	v_exp_f32_e32 v67, v67
	v_exp_f32_e32 v68, v68
	v_exp_f32_e32 v69, v69
	v_add_f32_e32 v230, v65, v64
	v_exp_f32_e32 v70, v70
	v_add_f32_e32 v230, v66, v230
	v_exp_f32_e32 v71, v71
	v_add_f32_e32 v230, v67, v230
	v_exp_f32_e32 v72, v72
	v_add_f32_e32 v230, v68, v230
	v_exp_f32_e32 v73, v73
	v_add_f32_e32 v230, v69, v230
	v_exp_f32_e32 v74, v74
	v_add_f32_e32 v230, v70, v230
	v_exp_f32_e32 v75, v75
	v_add_f32_e32 v230, v71, v230
	v_exp_f32_e32 v76, v76
	v_add_f32_e32 v230, v72, v230
	v_exp_f32_e32 v77, v77
	v_add_f32_e32 v230, v73, v230
	v_exp_f32_e32 v78, v78
	v_add_f32_e32 v230, v74, v230
	v_exp_f32_e32 v79, v79
	v_add_f32_e32 v230, v75, v230
	v_add_f32_e32 v230, v76, v230
	v_add_f32_e32 v230, v77, v230
	v_add_f32_e32 v230, v78, v230
	v_add_f32_e32 v230, v79, v230
	v_add_f32_e32 v173, v173, v230
	v_cvt_pk_bf16_f32 v64, v64, v65
	v_cvt_pk_bf16_f32 v65, v66, v67
	v_cvt_pk_bf16_f32 v66, v68, v69
	v_cvt_pk_bf16_f32 v67, v70, v71
	v_cvt_pk_bf16_f32 v68, v72, v73
	v_cvt_pk_bf16_f32 v69, v74, v75
	v_cvt_pk_bf16_f32 v70, v76, v77
	v_cvt_pk_bf16_f32 v71, v78, v79
	s_waitcnt lgkmcnt(0)
	ds_read_b128 v[230:233], v252 offset:128
	ds_read_b128 v[234:237], v253 offset:128
	ds_read_b128 v[238:241], v250 offset:256
	ds_read_b128 v[242:245], v251 offset:256
	ds_read_b128 v[246:249], v252 offset:256
	ds_read_b128 v[250:253], v253 offset:256
	s_setprio 2
	v_mfma_f32_32x32x16_bf16 v[48:63], v[64:67], v[198:201], v[48:63]
	v_mfma_f32_32x32x16_bf16 v[32:47], v[64:67], v[206:209], v[32:47]
	v_mfma_f32_32x32x16_bf16 v[16:31], v[64:67], v[214:217], v[16:31]
	v_mfma_f32_32x32x16_bf16 v[0:15], v[64:67], v[222:225], v[0:15]
	v_mfma_f32_32x32x16_bf16 v[48:63], v[68:71], v[202:205], v[48:63]
	v_mfma_f32_32x32x16_bf16 v[32:47], v[68:71], v[210:213], v[32:47]
	v_mfma_f32_32x32x16_bf16 v[16:31], v[68:71], v[218:221], v[16:31]
	v_mfma_f32_32x32x16_bf16 v[0:15], v[68:71], v[226:229], v[0:15]
	s_waitcnt lgkmcnt(0)
	v_mfma_f32_32x32x16_bf16 v[64:79], v[174:177], v[80:83], 0
	v_mfma_f32_32x32x16_bf16 v[64:79], v[178:181], v[84:87], v[64:79]
	v_mfma_f32_32x32x16_bf16 v[64:79], v[182:185], v[88:91], v[64:79]
	v_mfma_f32_32x32x16_bf16 v[64:79], v[186:189], v[92:95], v[64:79]
	v_mfma_f32_32x32x16_bf16 v[64:79], v[190:193], v[96:99], v[64:79]
	v_mfma_f32_32x32x16_bf16 v[64:79], v[194:197], v[100:103], v[64:79]
	v_mfma_f32_32x32x16_bf16 v[64:79], v[230:233], v[104:107], v[64:79]
	v_mfma_f32_32x32x16_bf16 v[64:79], v[234:237], v[108:111], v[64:79]
	v_mfma_f32_32x32x16_bf16 v[64:79], v[238:241], v[112:115], v[64:79]
	v_mfma_f32_32x32x16_bf16 v[64:79], v[242:245], v[116:119], v[64:79]
	v_mfma_f32_32x32x16_bf16 v[64:79], v[246:249], v[120:123], v[64:79]
	v_mfma_f32_32x32x16_bf16 v[64:79], v[250:253], v[124:127], v[64:79]
	s_add_i32 s43, s43, 1
	v_add_u32_e32 v136, s36, v136
	v_add_u32_e32 v138, s36, v138
	v_add_u32_e32 v140, s36, v140
	v_add_u32_e32 v142, s38, v142
	v_add_u32_e32 v144, s38, v144
	s_cmp_eq_u32 s43, 64
	s_mov_b32 s4, s0
	s_cbranch_scc0 .LBB0_1982
